# v26
# speedup vs baseline: 1.0235x; 1.0000x over previous
.Lq_role_done:
	s_mov_b32 s100, 0

.Lq_attn_q:
	s_getreg_b32 s12, hwreg(HW_REG_XCC_ID)
	s_add_u32 s12, s12, s100
	s_and_b32 s12, s12, 7
	s_lshl_b32 s101, s12, 2
	v_mov_b32_e32 v0, s101
	v_mov_b32_e32 v1, 1
	s_nop 0
	global_atomic_add v1, v0, v1, s[10:11] offset:16 sc0
	s_waitcnt vmcnt(0)
	v_readfirstlane_b32 s101, v1
	s_nop 3
	s_cmpk_lt_u32 s101, 0x300
	s_cbranch_scc0 .Lq_attn_nextq
	s_lshl_b32 s12, s12, 6
	s_lshr_b32 vcc_lo, s101, 6
	s_lshl_b32 vcc_lo, vcc_lo, 9
	s_and_b32 s101, s101, 63
	s_add_u32 s12, s12, vcc_lo
	s_add_u32 s12, s12, s101
	s_addk_i32 s12, 0xc0
	s_branch .Lq_publish
.Lq_attn_nextq:
	s_add_u32 s100, s100, 1
	s_cmp_lt_u32 s100, 8
	s_cbranch_scc1 .Lq_attn_q
	s_or_b32 s99, s99, 4
